# static priority raise for waves 4-7 also in the attention tile loop
# speedup vs baseline: 1.0136x; 1.0014x over previous
; DEV bf16x8 pack8(const float* x) { u32x4 o; o.x = pk2(x[0], x[1]); o.y = pk2(x[2], x[3]); o.z = pk2(x[4], x[5]); o.w = pk2(x[6], x[7]); return __builtin_bit_cast(bf16x8, o); }
; DEV void load_rope8(const Fr& F, const bf16_t* zp, int c8, int n, bool rope, float* o) {
;     unpack8(*(const u32x4*)(zp + c8), o);
;     if (rope) {
;         const bool second = (c8 & 16) != 0; float pr[8]; unpack8(*(const u32x4*)(zp + (second ? c8 - 16 : c8 + 16)), pr);
;         const int pos = (c8 >= 32) ? (n & 63) : (n >> 6); const float* tb = F.ROPE + (size_t)(pos * 16 + (c8 & 8)) * 2;
; #pragma unroll
;         for (int e = 0; e < 8; ++e) { const float c = tb[2 * e], s = tb[2 * e + 1]; o[e] = second ? (o[e] * c + pr[e] * s) : (o[e] * c - pr[e] * s); }
;     }
; }
; DEV void attn_item(const Fr& F, int l, int b, int qb, int kvh, bool ctxq) {
;     ...
;     const int qrow0 = b * RPB + (ctxq ? qb * 128 : CTXL + qb * 128);
;     const int g = w >> 2, rq = w & 3, r0 = rq * 32;
;     bf16x8 xq[2][2];
; #pragma unroll
;     for (int mt = 0; mt < 2; ++mt)
; #pragma unroll
;         for (int ks = 0; ks < 2; ++ks) { const int t = r0 + 16 * mt + fr; float x[8];
;             load_rope8(F, F.Z + (size_t)(qrow0 + t) * ZS + ZC_AQ + (kvh * 2 + g) * 64, 32 * ks + 8 * fq, qb * 128 + t, !ctxq, x);
; #pragma unroll
;             for (int e = 0; e < 8; ++e) x[e] *= 0.18033688011f;
;             xq[mt][ks] = pack8(x); }
;     const float sink = F.in[I_SINK][l * 4 + kvh * 2 + g] * 1.44269504089f;
;     float mrow[2], lrow[2]; f32x4 O[2][4];
; #pragma unroll
;     for (int mt = 0; mt < 2; ++mt) { mrow[mt] = sink; lrow[mt] = 1.f;
; #pragma unroll
;         for (int n = 0; n < 4; ++n) O[mt][n] = (f32x4){0.f, 0.f, 0.f, 0.f}; }
.LBB0_499:
	s_and_b64 vcc, exec, s[38:39]
	s_cbranch_vccz .LBB0_702
	s_lshr_b32 s63, s40, 8
	s_bfe_u32 s62, s40, 0x70001
	s_mulk_i32 s63, 0x4100
	s_lshl_b32 s7, s62, 7
	s_and_b32 s6, s40, 1
	s_add_i32 s38, s63, s7
	v_readlane_b32 s40, v239, 23
	s_add_i32 s44, s38, 0x100
	s_lshl_b32 s60, s6, 7
	v_readlane_b32 s38, v237, 7
	v_readlane_b32 s41, v239, 24
	s_add_i32 s38, s38, s60
	v_or_b32_e32 v180, s44, v203
	v_mov_b64_e32 v[2:3], s[40:41]
	s_movk_i32 s45, 0x1400
	s_ashr_i32 s39, s38, 31
	v_mad_i64_i32 v[4:5], s[40:41], v180, s45, v[2:3]
	s_lshl_b64 s[38:39], s[38:39], 1
	v_readlane_b32 s40, v237, 3
	s_waitcnt vmcnt(12)
	v_lshl_add_u64 v[32:33], v[4:5], 0, s[38:39]
	v_mov_b32_e32 v171, v0
	s_or_b32 s7, s40, s7
	v_lshl_add_u64 v[28:29], v[32:33], 0, v[170:171]
	v_lshl_add_u64 v[8:9], v[32:33], 0, v[172:173]
	s_lshl_b32 s7, s7, 1
	global_load_dwordx4 v[4:7], v[28:29], off offset:3104
	s_and_b32 s7, s7, 0x7f80
	global_load_dwordx4 v[8:11], v[8:9], off offset:3136
	v_readlane_b32 s40, v242, 28
	v_or_b32_e32 v1, s7, v204
	v_readlane_b32 s41, v242, 29
	s_nop 4
	global_load_dwordx4 v[24:27], v1, s[40:41]
	global_load_dwordx4 v[20:23], v1, s[40:41] offset:16
	global_load_dwordx4 v[16:19], v1, s[40:41] offset:32
	global_load_dwordx4 v[12:15], v1, s[40:41] offset:48
	s_nop 0
	global_load_dwordx4 v[28:31], v[28:29], off offset:3168
	v_mov_b32_e32 v175, v0
	v_lshl_add_u64 v[32:33], v[32:33], 0, v[174:175]
	global_load_dwordx4 v[32:35], v[32:33], off offset:3136
	s_nop 0
	global_load_dwordx4 v[36:39], v[156:157], off offset:16
	global_load_dwordx4 v[40:43], v[156:157], off
	global_load_dwordx4 v[44:47], v[156:157], off offset:48
	global_load_dwordx4 v[48:51], v[156:157], off offset:32
	v_or_b32_e32 v1, s44, v205
	s_waitcnt vmcnt(21)
	v_mad_i64_i32 v[52:53], s[40:41], v1, s45, v[2:3]
	v_lshl_add_u64 v[60:61], v[52:53], 0, s[38:39]
	v_lshl_add_u64 v[62:63], v[60:61], 0, v[170:171]
	s_waitcnt vmcnt(20)
	v_lshl_add_u64 v[56:57], v[60:61], 0, v[172:173]
	global_load_dwordx4 v[52:55], v[62:63], off offset:3104
	s_nop 0
	global_load_dwordx4 v[56:59], v[56:57], off offset:3136
	s_lshl_b32 s7, s6, 1
	v_readlane_b32 s6, v239, 55
	v_writelane_b32 v238, s7, 48
	s_or_b32 s6, s7, s6
	v_readlane_b32 s7, v237, 5
	v_readlane_b32 s80, v242, 10
	s_add_i32 s6, s6, s7
	v_readlane_b32 s81, v242, 11
	v_readlane_b32 s82, v242, 12
	v_readlane_b32 s83, v242, 13
	v_readlane_b32 s84, v242, 14
	v_readlane_b32 s85, v242, 15
	v_readlane_b32 s86, v242, 16
	v_readlane_b32 s87, v242, 17
	v_readlane_b32 s88, v242, 18
	v_readlane_b32 s89, v242, 19
	v_readlane_b32 s90, v242, 20
	v_readlane_b32 s91, v242, 21
	s_ashr_i32 s7, s6, 31
	v_readlane_b32 s92, v242, 22
	v_readlane_b32 s93, v242, 23
	v_readlane_b32 s94, v242, 24
	v_readlane_b32 s95, v242, 25
	s_mov_b64 s[80:81], s[84:85]
	s_lshl_b64 s[6:7], s[6:7], 2
	s_mov_b64 s[82:83], s[86:87]
	s_mov_b64 s[84:85], s[88:89]
	s_mov_b64 s[86:87], s[90:91]
	s_mov_b64 s[88:89], s[92:93]
	s_add_u32 s6, s88, s6
	s_addc_u32 s7, s89, s7
	v_ashrrev_i32_e32 v181, 31, v180
	s_movk_i32 s66, 0x1400
	v_lshl_add_u64 v[182:183], v[166:167], 0, s[60:61]
	s_mov_b32 s65, 0
	v_mov_b32_e32 v171, 1.0
	v_mov_b32_e32 v169, 1.0
	s_mov_b64 s[90:91], s[94:95]
	s_waitcnt vmcnt(13)
	v_lshlrev_b32_e32 v1, 16, v4
	v_and_b32_e32 v4, 0xffff0000, v4
	s_waitcnt vmcnt(12)
	v_lshlrev_b32_e32 v67, 16, v8
	v_and_b32_e32 v8, 0xffff0000, v8
	v_lshlrev_b32_e32 v68, 16, v9
	v_and_b32_e32 v9, 0xffff0000, v9
	v_lshlrev_b32_e32 v69, 16, v10
	v_and_b32_e32 v10, 0xffff0000, v10
	v_lshlrev_b32_e32 v70, 16, v11
	v_and_b32_e32 v11, 0xffff0000, v11
	s_waitcnt vmcnt(11)
	v_mul_f32_e32 v67, v25, v67
	v_mul_f32_e32 v8, v27, v8
	s_waitcnt vmcnt(10)
	v_mul_f32_e32 v68, v21, v68
	v_mul_f32_e32 v9, v23, v9
	s_waitcnt vmcnt(9)
	v_mul_f32_e32 v69, v17, v69
	v_mul_f32_e32 v10, v19, v10
	s_waitcnt vmcnt(8)
	v_mul_f32_e32 v70, v13, v70
	v_mul_f32_e32 v11, v15, v11
	v_lshlrev_b32_e32 v64, 16, v5
	v_and_b32_e32 v5, 0xffff0000, v5
	v_lshlrev_b32_e32 v65, 16, v6
	v_and_b32_e32 v6, 0xffff0000, v6
	v_lshlrev_b32_e32 v66, 16, v7
	v_and_b32_e32 v7, 0xffff0000, v7
	v_cndmask_b32_e64 v67, v67, -v67, s[46:47]
	v_cndmask_b32_e64 v8, v8, -v8, s[46:47]
	v_cndmask_b32_e64 v68, v68, -v68, s[46:47]
	v_cndmask_b32_e64 v9, v9, -v9, s[46:47]
	v_cndmask_b32_e64 v69, v69, -v69, s[46:47]
	v_cndmask_b32_e64 v10, v10, -v10, s[46:47]
	v_cndmask_b32_e64 v70, v70, -v70, s[46:47]
	v_cndmask_b32_e64 v11, v11, -v11, s[46:47]
	v_fmac_f32_e32 v67, v24, v1
	v_fmac_f32_e32 v8, v26, v4
	v_fmac_f32_e32 v68, v20, v64
	v_fmac_f32_e32 v9, v22, v5
	v_fmac_f32_e32 v69, v16, v65
	v_fmac_f32_e32 v10, v18, v6
	v_fmac_f32_e32 v70, v12, v66
	v_fmac_f32_e32 v11, v14, v7
	v_mul_f32_e32 v1, 0x3e38aa3b, v67
	v_mul_f32_e32 v4, 0x3e38aa3b, v8
	v_mul_f32_e32 v5, 0x3e38aa3b, v68
	v_mul_f32_e32 v6, 0x3e38aa3b, v9
	v_mul_f32_e32 v7, 0x3e38aa3b, v69
	v_mul_f32_e32 v8, 0x3e38aa3b, v10
	v_mul_f32_e32 v9, 0x3e38aa3b, v70
	v_mul_f32_e32 v10, 0x3e38aa3b, v11
	v_cvt_pk_bf16_f32 v4, v1, v4
	v_cvt_pk_bf16_f32 v5, v5, v6
	v_cvt_pk_bf16_f32 v6, v7, v8
	v_cvt_pk_bf16_f32 v7, v9, v10
	s_waitcnt vmcnt(7)
	v_lshlrev_b32_e32 v1, 16, v28
	v_and_b32_e32 v8, 0xffff0000, v28
	v_lshlrev_b32_e32 v9, 16, v29
	v_and_b32_e32 v10, 0xffff0000, v29
	v_lshlrev_b32_e32 v11, 16, v30
	v_and_b32_e32 v28, 0xffff0000, v30
	v_lshlrev_b32_e32 v29, 16, v31
	v_and_b32_e32 v30, 0xffff0000, v31
	s_waitcnt vmcnt(6)
	v_lshlrev_b32_e32 v31, 16, v32
	s_waitcnt vmcnt(4)
; #define LAS __attribute__((address_space(3)))
; DEV bf16x8 pack8(const float* x) { u32x4 o; o.x = pk2(x[0], x[1]); o.y = pk2(x[2], x[3]); o.z = pk2(x[4], x[5]); o.w = pk2(x[6], x[7]); return __builtin_bit_cast(bf16x8, o); }
; DEV void attn_item(const Fr& F, int l, int b, int qb, int kvh, bool ctxq) {
;     ...
;     bf16x8 xq[2][2];
; #pragma unroll
;     for (int mt = 0; mt < 2; ++mt)
; #pragma unroll
;         for (int ks = 0; ks < 2; ++ks) { const int t = r0 + 16 * mt + fr; float x[8];
;             load_rope8(F, F.Z + (size_t)(qrow0 + t) * ZS + ZC_AQ + (kvh * 2 + g) * 64, 32 * ks + 8 * fq, qb * 128 + t, !ctxq, x);
; #pragma unroll
;             for (int e = 0; e < 8; ++e) x[e] *= 0.18033688011f;
;             xq[mt][ks] = pack8(x); }
;     const float sink = F.in[I_SINK][l * 4 + kvh * 2 + g] * 1.44269504089f;
;     float mrow[2], lrow[2]; f32x4 O[2][4];
; #pragma unroll
;     for (int mt = 0; mt < 2; ++mt) { mrow[mt] = sink; lrow[mt] = 1.f;
; #pragma unroll
;         for (int n = 0; n < 4; ++n) O[mt][n] = (f32x4){0.f, 0.f, 0.f, 0.f}; }
;     LAS bf16_t* Pw = Ps + w * 32 * 136;
;     const int ktl[5] = {0, 1, 2, 3, 4};
;     int kt = 0; const int nkt = ctxq ? 2 : 5;
;     u32x4 rk[2], rp[2], rv[2];
;     auto tile_ok = [&](int k) { const int kb = qb + k - 3; return k < 2 || (kb >= 0 && kb < SEQ / 128); };
;     ...
;     (void)ktl;
;     while (kt < nkt && !tile_ok(kt)) ++kt;
;     if (kt < nkt) ATT_PREFETCH(kt);
	v_mul_f32_e32 v31, v41, v31
	v_and_b32_e32 v32, 0xffff0000, v32
	v_cndmask_b32_e64 v31, v31, -v31, s[46:47]
	v_fmac_f32_e32 v31, v40, v1
	v_mul_f32_e32 v1, v43, v32
	v_lshlrev_b32_e32 v64, 16, v33
	v_cndmask_b32_e64 v1, v1, -v1, s[46:47]
	v_fmac_f32_e32 v1, v42, v8
	v_mul_f32_e32 v8, v37, v64
	v_and_b32_e32 v33, 0xffff0000, v33
	v_cndmask_b32_e64 v8, v8, -v8, s[46:47]
	v_fmac_f32_e32 v8, v36, v9
	v_mul_f32_e32 v9, v39, v33
	v_lshlrev_b32_e32 v65, 16, v34
	v_cndmask_b32_e64 v9, v9, -v9, s[46:47]
	v_fmac_f32_e32 v9, v38, v10
	s_waitcnt vmcnt(2)
	v_mul_f32_e32 v10, v49, v65
	v_and_b32_e32 v34, 0xffff0000, v34
	v_cndmask_b32_e64 v10, v10, -v10, s[46:47]
	v_fmac_f32_e32 v10, v48, v11
	v_mul_f32_e32 v11, v51, v34
	v_lshlrev_b32_e32 v66, 16, v35
	v_cndmask_b32_e64 v11, v11, -v11, s[46:47]
	v_fmac_f32_e32 v11, v50, v28
	v_mul_f32_e32 v28, v45, v66
	v_and_b32_e32 v35, 0xffff0000, v35
	v_cndmask_b32_e64 v28, v28, -v28, s[46:47]
	v_fmac_f32_e32 v28, v44, v29
	v_mul_f32_e32 v29, v47, v35
	v_cndmask_b32_e64 v29, v29, -v29, s[46:47]
	v_fmac_f32_e32 v29, v46, v30
	v_mul_f32_e32 v10, 0x3e38aa3b, v10
	v_mul_f32_e32 v11, 0x3e38aa3b, v11
	v_mul_f32_e32 v28, 0x3e38aa3b, v28
	v_mul_f32_e32 v29, 0x3e38aa3b, v29
	v_cvt_pk_bf16_f32 v10, v10, v11
	v_cvt_pk_bf16_f32 v11, v28, v29
	v_lshl_add_u64 v[28:29], v[60:61], 0, v[174:175]
	global_load_dwordx4 v[40:43], v[62:63], off offset:3168
	v_mul_f32_e32 v1, 0x3e38aa3b, v1
	global_load_dwordx4 v[60:63], v[28:29], off offset:3136
	global_load_dwordx4 v[64:67], v[158:159], off offset:16
	global_load_dwordx4 v[68:71], v[158:159], off
	s_waitcnt vmcnt(4)
	v_lshlrev_b32_e32 v28, 16, v56
	v_lshlrev_b32_e32 v37, 16, v57
	v_mul_f32_e32 v25, v25, v28
	v_mul_f32_e32 v30, 0x3e38aa3b, v31
	v_mul_f32_e32 v31, 0x3e38aa3b, v8
	v_mul_f32_e32 v9, 0x3e38aa3b, v9
	v_cvt_pk_bf16_f32 v8, v30, v1
	v_lshlrev_b32_e32 v1, 16, v52
	v_and_b32_e32 v29, 0xffff0000, v56
	v_lshlrev_b32_e32 v39, 16, v58
	v_cndmask_b32_e64 v28, v25, -v25, s[46:47]
	v_mul_f32_e32 v21, v21, v37
	v_cvt_pk_bf16_f32 v9, v31, v9
	v_lshlrev_b32_e32 v31, 16, v53
	v_and_b32_e32 v38, 0xffff0000, v57
	v_fmac_f32_e32 v28, v24, v1
	v_mul_f32_e32 v1, v27, v29
	v_cndmask_b32_e64 v29, v21, -v21, s[46:47]
	v_mul_f32_e32 v17, v17, v39
	v_lshlrev_b32_e32 v33, 16, v54
	v_and_b32_e32 v44, 0xffff0000, v58
	v_fmac_f32_e32 v29, v20, v31
	v_mul_f32_e32 v20, v23, v38
	v_cndmask_b32_e64 v38, v17, -v17, s[46:47]
	v_and_b32_e32 v30, 0xffff0000, v52
	v_and_b32_e32 v32, 0xffff0000, v53
	v_lshlrev_b32_e32 v45, 16, v59
	v_cndmask_b32_e64 v1, v1, -v1, s[46:47]
	v_cndmask_b32_e64 v37, v20, -v20, s[46:47]
	v_fmac_f32_e32 v38, v16, v33
	v_mul_f32_e32 v16, v19, v44
	v_and_b32_e32 v34, 0xffff0000, v54
	v_fmac_f32_e32 v1, v26, v30
	v_fmac_f32_e32 v37, v22, v32
	global_load_dwordx4 v[20:23], v[158:159], off offset:48
	global_load_dwordx4 v[24:27], v[158:159], off offset:32
	v_cndmask_b32_e64 v19, v16, -v16, s[46:47]
	v_mul_f32_e32 v13, v13, v45
	v_lshlrev_b32_e32 v35, 16, v55
	v_and_b32_e32 v46, 0xffff0000, v59
	v_fmac_f32_e32 v19, v18, v34
	v_cndmask_b32_e64 v18, v13, -v13, s[46:47]
	v_fmac_f32_e32 v18, v12, v35
	v_mul_f32_e32 v12, v15, v46
	v_cndmask_b32_e64 v39, v12, -v12, s[46:47]
	v_add_u32_e32 v12, s63, v141
	v_and_b32_e32 v36, 0xffff0000, v55
	global_load_dword v76, v0, s[6:7]
	v_mad_i64_i32 v[12:13], s[6:7], v12, s45, v[2:3]
	v_fmac_f32_e32 v39, v14, v36
	v_lshl_add_u64 v[12:13], v[12:13], 0, s[60:61]
	v_lshlrev_b32_e32 v14, 1, v150
	v_mov_b32_e32 v15, v0
	v_lshl_add_u64 v[12:13], v[12:13], 0, v[14:15]
	v_mul_f32_e32 v36, 0x3e38aa3b, v28
	v_mul_f32_e32 v72, 0x3e38aa3b, v29
	v_lshl_add_u64 v[16:17], v[12:13], 0, v[178:179]
	global_load_dwordx4 v[28:31], v[12:13], off offset:3616
	global_load_dwordx4 v[32:35], v[12:13], off offset:3872
	v_add_u32_e32 v12, s63, v151
	v_mad_i64_i32 v[2:3], s[6:7], v12, s45, v[2:3]
	v_lshl_add_u64 v[2:3], v[2:3], 0, s[60:61]
	v_lshl_add_u64 v[2:3], v[2:3], 0, v[14:15]
	v_lshl_add_u64 v[12:13], v[2:3], 0, v[178:179]
	global_load_dwordx4 v[44:47], v[16:17], off offset:3616
	global_load_dwordx4 v[48:51], v[2:3], off offset:3616
	global_load_dwordx4 v[52:55], v[12:13], off offset:3616
	global_load_dwordx4 v[56:59], v[2:3], off offset:3872
	v_mul_f32_e32 v1, 0x3e38aa3b, v1
	v_mul_f32_e32 v13, 0x3e38aa3b, v18
	v_cvt_pk_bf16_f32 v36, v36, v1
	v_mul_f32_e32 v2, 0x3e38aa3b, v37
	v_mul_f32_e32 v12, 0x3e38aa3b, v19
	v_cvt_pk_bf16_f32 v37, v72, v2
	v_mul_f32_e32 v3, 0x3e38aa3b, v38
	v_cvt_pk_bf16_f32 v38, v3, v12
	v_mul_f32_e32 v14, 0x3e38aa3b, v39
	v_cvt_pk_bf16_f32 v39, v13, v14
	s_waitcnt vmcnt(12)
	v_lshlrev_b32_e32 v1, 16, v40
	v_and_b32_e32 v2, 0xffff0000, v40
	s_waitcnt vmcnt(11)
	v_lshlrev_b32_e32 v17, 16, v60
	s_waitcnt vmcnt(9)
	v_mul_f32_e32 v17, v69, v17
	v_and_b32_e32 v18, 0xffff0000, v60
	v_cndmask_b32_e64 v17, v17, -v17, s[46:47]
	v_fmac_f32_e32 v17, v68, v1
	v_mul_f32_e32 v1, v71, v18
	v_lshlrev_b32_e32 v19, 16, v61
	v_cndmask_b32_e64 v1, v1, -v1, s[46:47]
	v_fmac_f32_e32 v1, v70, v2
	v_mul_f32_e32 v2, v65, v19
	v_lshlrev_b32_e32 v3, 16, v41
	v_and_b32_e32 v40, 0xffff0000, v61
	v_cndmask_b32_e64 v2, v2, -v2, s[46:47]
	v_fmac_f32_e32 v2, v64, v3
	v_mul_f32_e32 v3, v67, v40
	v_and_b32_e32 v12, 0xffff0000, v41
	v_lshlrev_b32_e32 v41, 16, v62
	v_cndmask_b32_e64 v3, v3, -v3, s[46:47]
	v_fmac_f32_e32 v3, v66, v12
	v_lshlrev_b32_e32 v13, 16, v42
	v_and_b32_e32 v14, 0xffff0000, v42
	v_and_b32_e32 v42, 0xffff0000, v62
	v_lshlrev_b32_e32 v15, 16, v43
	v_and_b32_e32 v16, 0xffff0000, v43
	v_lshlrev_b32_e32 v43, 16, v63
	v_and_b32_e32 v60, 0xffff0000, v63
	v_mul_f32_e32 v2, 0x3e38aa3b, v2
	v_mul_f32_e32 v3, 0x3e38aa3b, v3
	v_mul_f32_e32 v1, 0x3e38aa3b, v1
	v_cvt_pk_bf16_f32 v73, v2, v3
	v_mov_b32_e32 v2, v0
	v_mov_b32_e32 v3, v0
	s_add_i32 s60, s62, -2
	s_waitcnt vmcnt(7)
	v_mul_f32_e32 v12, v25, v41
	v_cndmask_b32_e64 v12, v12, -v12, s[46:47]
	v_fmac_f32_e32 v12, v24, v13
	v_mul_f32_e32 v13, v27, v42
	v_cndmask_b32_e64 v13, v13, -v13, s[46:47]
	v_fmac_f32_e32 v13, v26, v14
	v_mul_f32_e32 v14, v21, v43
	v_cndmask_b32_e64 v14, v14, -v14, s[46:47]
	v_fmac_f32_e32 v14, v20, v15
	v_mul_f32_e32 v15, v23, v60
	v_cndmask_b32_e64 v15, v15, -v15, s[46:47]
	v_fmac_f32_e32 v15, v22, v16
	v_mul_f32_e32 v16, 0x3e38aa3b, v17
	v_mul_f32_e32 v12, 0x3e38aa3b, v12
	v_mul_f32_e32 v13, 0x3e38aa3b, v13
	v_mul_f32_e32 v14, 0x3e38aa3b, v14
	v_mul_f32_e32 v15, 0x3e38aa3b, v15
	v_cvt_pk_bf16_f32 v72, v16, v1
	v_cvt_pk_bf16_f32 v74, v12, v13
	v_cvt_pk_bf16_f32 v75, v14, v15
	s_waitcnt vmcnt(6)
	v_mul_f32_e32 v175, 0x3fb8aa3b, v76
	v_mov_b32_e32 v1, v0
	v_mov_b64_e32 v[14:15], v[2:3]
	v_mov_b64_e32 v[18:19], v[2:3]
	v_mov_b64_e32 v[22:23], v[2:3]
	v_mov_b64_e32 v[26:27], v[2:3]
	v_mov_b64_e32 v[42:43], v[2:3]
	v_mov_b64_e32 v[62:63], v[2:3]
	v_mov_b64_e32 v[66:67], v[2:3]
	v_mov_b64_e32 v[70:71], v[2:3]
	v_mov_b32_e32 v177, v175
	v_mov_b64_e32 v[12:13], v[0:1]
	v_mov_b64_e32 v[16:17], v[0:1]
	v_mov_b64_e32 v[20:21], v[0:1]
	v_mov_b64_e32 v[24:25], v[0:1]
	v_mov_b64_e32 v[40:41], v[0:1]
	v_mov_b64_e32 v[60:61], v[0:1]
	v_mov_b64_e32 v[64:65], v[0:1]
	v_mov_b64_e32 v[68:69], v[0:1]
; DEV void attn_item(const Fr& F, int l, int b, int qb, int kvh, bool ctxq) {
;     ...
;     while (kt < nkt) {
;         const int kb = qb + kt - 3; const bool rope = kt >= 2;
;         __syncthreads();
; #pragma unroll
;         for (int i = 0; i < 2; ++i) { const int idx = tid + NTHR * i; const int s_ = idx >> 3, c8 = (idx & 7) * 8;
;             float x[8]; unpack8(rk[i], x);
;             if (rope) { float pr[8]; unpack8(rp[i], pr); const bool second = (c8 & 16) != 0; const int n = kb * 128 + s_;
;                 const int pos = (c8 >= 32) ? (n & 63) : (n >> 6); const float* tb = F.ROPE + (size_t)(pos * 16 + (c8 & 8)) * 2;
; #pragma unroll
;                 for (int e = 0; e < 8; ++e) { const float c = tb[2 * e], sn = tb[2 * e + 1]; x[e] = second ? (x[e] * c + pr[e] * sn) : (x[e] * c - pr[e] * sn); } }
.LBB0_501:
	v_readfirstlane_b32 s100, v188
	s_bitcmp1_b32 s100, 8
	s_cbranch_scc0 .Lprio_skip_att
	s_setprio 1
.Lprio_skip_att:
	s_add_i32 s6, s65, s62
	s_cmp_gt_i32 s65, 1
	s_cselect_b64 s[38:39], -1, 0
	s_lshl_b32 s6, s6, 7
	s_addk_i32 s6, 0xfe80
	s_waitcnt vmcnt(5)
	s_cmp_lt_i32 s65, 2
	s_cbranch_scc1 .Lrp_skip
	v_readlane_b32 s40, v242, 28
	v_readlane_b32 s41, v242, 29
	v_add_u32_e32 v1, s6, v141
	v_ashrrev_i32_e32 v1, 6, v1
	v_cndmask_b32_e64 v1, v1, v208, s[50:51]
	v_lshl_or_b32 v82, v1, 4, v206
	v_ashrrev_i32_e32 v83, 31, v82
	v_lshl_add_u64 v[94:95], v[82:83], 3, s[40:41]
	global_load_dwordx4 v[82:85], v[94:95], off offset:48
	global_load_dwordx4 v[86:89], v[94:95], off offset:32
	global_load_dwordx4 v[90:93], v[94:95], off offset:16
	s_nop 0
	global_load_dwordx4 v[94:97], v[94:95], off
	v_add_u32_e32 v1, s6, v151
	v_ashrrev_i32_e32 v1, 6, v1
	v_cndmask_b32_e64 v1, v1, v161, s[50:51]
	v_lshl_or_b32 v102, v1, 4, v206
	v_ashrrev_i32_e32 v103, 31, v102
	v_lshl_add_u64 v[114:115], v[102:103], 3, s[40:41]
	global_load_dwordx4 v[102:105], v[114:115], off offset:48
	global_load_dwordx4 v[106:109], v[114:115], off offset:32
	global_load_dwordx4 v[110:113], v[114:115], off offset:16
	s_nop 0
	global_load_dwordx4 v[114:117], v[114:115], off

; DEV unsigned pk2(float lo, float hi) { unsigned r; asm("v_cvt_pk_bf16_f32 %0, %1, %2" : "=v"(r) : "v"(lo), "v"(hi)); return r; }
; DEV void attn_item(const Fr& F, int l, int b, int qb, int kvh, bool ctxq) {
;     ...
; #pragma unroll
;     for (int mt = 0; mt < 2; ++mt) { const int t = r0 + mt * 16 + fr; const float rl = 1.f / lrow[mt];
; #pragma unroll
;         for (int n2 = 0; n2 < 4; ++n2) { u32x2 wv; wv.x = pk2(O[mt][n2][0] * rl, O[mt][n2][1] * rl); wv.y = pk2(O[mt][n2][2] * rl, O[mt][n2][3] * rl);
;             *(u32x2*)(F.MIX + (size_t)(qrow0 + t) * D + 512 + (kvh * 2 + g) * 64 + n2 * 16 + 4 * fq) = wv; } }
;     __syncthreads();
.LBB0_701:
	s_setprio 0
	v_div_scale_f32 v1, s[6:7], v3, v3, 1.0
	v_rcp_f32_e32 v2, v1
	v_readlane_b32 s6, v237, 5
	v_readlane_b32 s7, v238, 48
	s_add_i32 s6, s6, s7
	v_fma_f32 v4, -v1, v2, 1.0
	v_fmac_f32_e32 v2, v4, v2
	v_div_scale_f32 v4, vcc, 1.0, v3, 1.0
	v_mul_f32_e32 v5, v4, v2
	v_fma_f32 v6, -v1, v5, v4
	v_fmac_f32_e32 v5, v6, v2
	v_fma_f32 v1, -v1, v5, v4
	s_lshl_b32 s6, s6, 6
	v_div_fmas_f32 v1, v1, v2, v5
	v_readlane_b32 s40, v239, 25
	s_ashr_i32 s7, s6, 31
	v_div_fixup_f32 v1, v1, v3, 1.0
	v_lshlrev_b64 v[2:3], 11, v[180:181]
	v_readlane_b32 s41, v239, 26
	v_mul_f32_e32 v4, v1, v68
	v_mul_f32_e32 v5, v1, v69
	v_lshl_add_u64 v[2:3], s[40:41], 0, v[2:3]
	s_lshl_b64 s[6:7], s[6:7], 1
	v_cvt_pk_bf16_f32 v4, v4, v5
	v_mul_f32_e32 v5, v1, v70
	v_lshl_add_u64 v[2:3], v[2:3], 0, s[6:7]
	v_mov_b32_e32 v177, v0
	v_mul_f32_e32 v6, v1, v71
	v_cvt_pk_bf16_f32 v5, v5, v6
	v_lshl_add_u64 v[2:3], v[2:3], 0, v[176:177]
	global_store_dwordx2 v[2:3], v[4:5], off offset:1024
	v_mul_f32_e32 v4, v1, v64
	v_mul_f32_e32 v5, v1, v65
	v_cvt_pk_bf16_f32 v4, v4, v5
	v_mul_f32_e32 v5, v1, v66
	v_mul_f32_e32 v6, v1, v67
	v_cvt_pk_bf16_f32 v5, v5, v6
	global_store_dwordx2 v[2:3], v[4:5], off offset:1056
	v_mul_f32_e32 v4, v1, v60
	v_mul_f32_e32 v5, v1, v61
	v_cvt_pk_bf16_f32 v4, v4, v5
	v_mul_f32_e32 v5, v1, v62
	v_mul_f32_e32 v6, v1, v63
	v_cvt_pk_bf16_f32 v5, v5, v6
	v_div_scale_f32 v6, s[38:39], v77, v77, 1.0
	v_rcp_f32_e32 v7, v6
	global_store_dwordx2 v[2:3], v[4:5], off offset:1088
	v_mul_f32_e32 v4, v1, v40
	v_mul_f32_e32 v5, v1, v41
	v_cvt_pk_bf16_f32 v4, v4, v5
	v_mul_f32_e32 v5, v1, v42
	v_mul_f32_e32 v1, v1, v43
	v_cvt_pk_bf16_f32 v5, v5, v1
	v_fma_f32 v1, -v6, v7, 1.0
	v_fmac_f32_e32 v7, v1, v7
	v_div_scale_f32 v1, vcc, 1.0, v77, 1.0
	global_store_dwordx2 v[2:3], v[4:5], off offset:1120
	v_mul_f32_e32 v2, v1, v7
	v_fma_f32 v3, -v6, v2, v1
	v_fmac_f32_e32 v2, v3, v7
	v_fma_f32 v1, -v6, v2, v1
	v_div_fmas_f32 v1, v1, v7, v2
	v_or_b32_e32 v2, 16, v180
	v_ashrrev_i32_e32 v3, 31, v2
	v_div_fixup_f32 v1, v1, v77, 1.0
	v_lshlrev_b64 v[2:3], 11, v[2:3]
	v_mul_f32_e32 v4, v1, v24
	v_mul_f32_e32 v5, v1, v25
	v_lshl_add_u64 v[2:3], s[40:41], 0, v[2:3]
	v_cvt_pk_bf16_f32 v4, v4, v5
	v_mul_f32_e32 v5, v1, v26
	v_lshl_add_u64 v[2:3], v[2:3], 0, s[6:7]
	v_mul_f32_e32 v6, v1, v27
	v_cvt_pk_bf16_f32 v5, v5, v6
	v_lshl_add_u64 v[2:3], v[2:3], 0, v[176:177]
	global_store_dwordx2 v[2:3], v[4:5], off offset:1024
	v_mul_f32_e32 v4, v1, v20
	v_mul_f32_e32 v5, v1, v21
	v_cvt_pk_bf16_f32 v4, v4, v5
	v_mul_f32_e32 v5, v1, v22
	v_mul_f32_e32 v6, v1, v23
	v_cvt_pk_bf16_f32 v5, v5, v6
	global_store_dwordx2 v[2:3], v[4:5], off offset:1056
	v_mul_f32_e32 v4, v1, v16
	v_mul_f32_e32 v5, v1, v17
	v_cvt_pk_bf16_f32 v4, v4, v5
	v_mul_f32_e32 v5, v1, v18
	v_mul_f32_e32 v6, v1, v19
	v_cvt_pk_bf16_f32 v5, v5, v6
	global_store_dwordx2 v[2:3], v[4:5], off offset:1088
	v_mul_f32_e32 v4, v1, v12
	v_mul_f32_e32 v5, v1, v13
	v_cvt_pk_bf16_f32 v4, v4, v5
	v_mul_f32_e32 v5, v1, v14
	s_mov_b64 s[6:7], -1
	v_mul_f32_e32 v1, v1, v15
	v_cvt_pk_bf16_f32 v5, v5, v1
	global_store_dwordx2 v[2:3], v[4:5], off offset:1120
	s_barrier
